# overlay-hazard guard: G3 / G1 first epilogue waits until every XCD passed the preceding local barrier (h overlays UV|Gb|CAT|Q|K|V|O); stress-tested with heavy XCD skew
# speedup vs baseline: 1.0049x; 1.0002x over previous
; #define LAS __attribute__((address_space(3)))
; __global__ void __launch_bounds__(NTHR, 2) mega_fwd(Args A) {
;     extern __shared__ __attribute__((aligned(16))) unsigned char lds_raw[];
;     LAS unsigned char* lds = (LAS unsigned char*)lds_raw;
;     const int G = gridDim.x, bx = blockIdx.x;
;     volatile LAS unsigned* bst = (volatile LAS unsigned*)(lds + LDS_BYTES - 16);
;     if (threadIdx.x < 4) bst[threadIdx.x] = 0u;
;     __syncthreads();
;     XcdBarrier bar; bar.bar = (unsigned*)A.ws; bar.x = 0; bar.st = bst;
;     if (A.coop) bar = xcd_barrier_post((unsigned*)A.ws, bst);
_Z8mega_fwd4Args:
	s_mov_b32 s101, 0
	s_load_dwordx8 s[4:11], s[0:1], 0x80
	s_mov_b32 s67, s2
	s_load_dwordx2 s[2:3], s[0:1], 0xa0
	v_and_b32_e32 v240, 0x3ff, v0
	v_cmp_gt_u32_e32 vcc, 4, v240
	s_waitcnt lgkmcnt(0)
	v_writelane_b32 v252, s4, 0
	s_nop 1
	v_writelane_b32 v252, s5, 1
	v_writelane_b32 v252, s6, 2
	v_writelane_b32 v252, s7, 3
	v_writelane_b32 v252, s8, 4
	v_writelane_b32 v252, s9, 5
	v_writelane_b32 v252, s10, 6
	v_writelane_b32 v252, s11, 7
	v_writelane_b32 v252, s2, 8
	s_nop 1
	v_writelane_b32 v252, s3, 9
	s_load_dwordx4 s[40:43], s[0:1], 0xa8
	s_load_dword s2, s[0:1], 0xb8
	s_waitcnt lgkmcnt(0)
	v_writelane_b32 v252, s2, 10
	s_add_u32 s2, s0, 0xb8
	s_addc_u32 s3, s1, 0
	v_writelane_b32 v252, s2, 11
	s_nop 1
	v_writelane_b32 v252, s3, 12
	s_and_saveexec_b64 s[4:5], vcc
	v_lshl_add_u32 v1, v240, 2, 0
	v_add_u32_e32 v1, 0x21ff0, v1
	v_mov_b32_e32 v2, 0
	ds_write_b32 v1, v2
	s_or_b64 exec, exec, s[4:5]
	s_cmp_lg_u32 s40, 0
	s_cselect_b64 s[4:5], -1, 0
	v_writelane_b32 v252, s4, 13
	s_mov_b32 s2, 0
	s_cmp_eq_u32 s40, 0
	v_writelane_b32 v252, s5, 14
	v_cmp_eq_u32_e32 vcc, 0, v240
	s_waitcnt lgkmcnt(0)
	s_barrier
	s_cbranch_scc1 .LBB0_7
	s_getreg_b32 s2, hwreg(HW_REG_XCC_ID, 0, 4)
	s_and_b32 s2, s2, 15
	s_and_saveexec_b64 s[4:5], vcc
	s_cbranch_execz .LBB0_6
	s_mov_b64 s[6:7], exec
	v_mbcnt_lo_u32_b32 v1, s6, 0
	v_mbcnt_hi_u32_b32 v1, s7, v1
	v_cmp_eq_u32_e32 vcc, 0, v1
	s_and_b64 s[8:9], exec, vcc
	s_mov_b64 exec, s[8:9]
	s_cbranch_execz .LBB0_6
	s_bcnt1_i32_b64 s6, s[6:7]
	v_mov_b32_e32 v2, s6
	s_load_dwordx2 s[6:7], s[0:1], 0xa0
	s_lshl_b32 s3, s2, 8
	v_mov_b32_e32 v1, s3
	s_waitcnt lgkmcnt(0)
	global_atomic_add v1, v2, s[6:7] offset:1024

; __device__ __forceinline__ unsigned xb_ld(unsigned* p)              { return __hip_atomic_load(p, __ATOMIC_RELAXED, __HIP_MEMORY_SCOPE_AGENT); }
; __device__ __forceinline__ unsigned xb_add(unsigned* p, unsigned v) { return __hip_atomic_fetch_add(p, v, __ATOMIC_RELAXED, __HIP_MEMORY_SCOPE_AGENT); }
; #define XB_SPIN(cond, bar) do { unsigned _sp = 0; while (cond) { __builtin_amdgcn_s_sleep(1); \
;     if ((++_sp & 255u) == 0u) { if (xb_ld(&(bar)[XB_TMO])) break; if (_sp > XB_SPIN_CAP) { atomicAdd(&(bar)[XB_TMO], 1u); break; } } } } while (0)
; __device__ __forceinline__ void xcd_barrier(const XcdBarrier& b) {
;     asm volatile("s_waitcnt vmcnt(0)" ::: "memory");
;     __syncthreads();
;     if (threadIdx.x == 0) {
;         unsigned* bar = b.bar;
;         __builtin_amdgcn_s_waitcnt(0);
;         unsigned nloc = b.st[0], nx = b.st[1];
;         if (nloc == 0u) { xcd_barrier_complete(bar, b.x, nloc, nx); b.st[0] = nloc; b.st[1] = nx; }
;         const unsigned old = xb_add(&bar[XB_XSUB(b.x)], 1u);
;         const unsigned gen = old / nloc;
;         if (old + 1u == (gen + 1u) * nloc) {
;             __builtin_amdgcn_fence(__ATOMIC_RELEASE, "agent");
;             asm volatile("s_waitcnt vmcnt(0)" ::: "memory");
;             const unsigned og = xb_add(&bar[XB_TOP], 1u);
;             const unsigned tg = og / nx;
;             if (og + 1u == (tg + 1u) * nx) xb_add(&bar[XB_TOPGEN], 1u);
;             else XB_SPIN(xb_ld(&bar[XB_TOPGEN]) == tg, bar);
;             __builtin_amdgcn_fence(__ATOMIC_ACQUIRE, "agent");
;             asm volatile("s_waitcnt vmcnt(0)" ::: "memory");
;         } else {
;             XB_SPIN(xb_ld(&bar[XB_TOPGEN]) == gen, bar);
.LBB0_93:
	s_and_b32 s98, s67, 7
	s_lshl_b32 s98, s98, 2
	s_add_i32 s98, s98, 0x3600
	s_lshl_b32 s99, 1, s2
	v_mov_b32_e32 v6, s98
	v_mov_b32_e32 v7, s99
	v_readlane_b32 s98, v252, 8
	v_readlane_b32 s99, v252, 9
	s_nop 4
	global_atomic_or v6, v7, s[98:99]
	s_waitcnt vmcnt(0)
	s_lshl_b32 s3, s2, 8
	v_readlane_b32 s4, v252, 8
	v_readlane_b32 s5, v252, 9
	s_add_u32 s4, s4, s3
	s_addc_u32 s5, s5, 0
	v_mov_b32_e32 v2, 0x1000
	v_mov_b32_e32 v4, 1
	v_sub_u32_e32 v5, 0, v3
	global_atomic_add v4, v2, v4, s[4:5] offset:1024 sc0
	v_cvt_f32_u32_e32 v2, v3
	v_rcp_iflag_f32_e32 v2, v2
	s_nop 0
	v_mul_f32_e32 v2, 0x4f7ffffe, v2
	v_cvt_u32_f32_e32 v2, v2
	v_mul_lo_u32 v5, v5, v2
	v_mul_hi_u32 v5, v2, v5
	v_add_u32_e32 v2, v2, v5
	s_waitcnt vmcnt(0)
	v_mul_hi_u32 v2, v4, v2
	v_mul_lo_u32 v5, v2, v3
	v_sub_u32_e32 v5, v4, v5
	v_add_u32_e32 v6, 1, v2
	v_cmp_ge_u32_e32 vcc, v5, v3
	v_add_u32_e32 v4, 1, v4
	s_nop 0
	v_cndmask_b32_e32 v2, v2, v6, vcc
	v_sub_u32_e32 v6, v5, v3
	v_cndmask_b32_e32 v5, v5, v6, vcc
	v_add_u32_e32 v6, 1, v2
	v_cmp_ge_u32_e32 vcc, v5, v3
	s_nop 1
	v_cndmask_b32_e32 v2, v2, v6, vcc
	v_mul_lo_u32 v5, v3, v2
	v_add_u32_e32 v3, v5, v3
	v_cmp_ne_u32_e32 vcc, v4, v3
	s_waitcnt lgkmcnt(0)
	v_add_u32_e32 v5, 1, v2
	v_mul_lo_u32 v5, v5, v1
	v_readlane_b32 s98, v252, 8
	v_readlane_b32 s99, v252, 9
	v_mov_b32_e32 v7, 0x3400
	v_mov_b32_e32 v8, 1
	s_nop 4
	s_cbranch_vccnz .Lxb_p0_nl
	buffer_wbl2 sc1
	s_waitcnt vmcnt(0)
	global_atomic_add v7, v8, s[98:99]
	buffer_inv sc1
	s_branch .Lxb_p0_poll

; __global__ void __launch_bounds__(NTHR, 2) mega_fwd(Args A) {
;     ...
;     for (int layer = 0; layer < 4; ++layer) {
;         const int li = layer >> 1; const bool even = (layer & 1) == 0;
;         PHASE_BEGIN
.LBB0_128:
	s_or_b64 exec, exec, s[0:1]
	s_waitcnt lgkmcnt(0)
	s_barrier
	s_mov_b32 s101, 1

; #define PG8_BAR __builtin_amdgcn_s_barrier()
; template <class Epi, class Sched, bool ALIGN_EPI = false, bool SP2 = false>
; __device__ __forceinline__ void gemm_phase(PG8_LAS unsigned char* lds, const Gemm g, const Sched& S, const Epi& E) {
;     ...
;         if constexpr (ALIGN_EPI) { if (wr == 0) PG8_BAR; }
;         if constexpr (!Epi::AFTER_DRAIN) { E(acc, cur, wr, wc, fr, fq); S.done(cur); }
.LBB0_146:
	s_cmp_eq_u32 s101, 0
	s_cbranch_scc1 .Lxc_skip_0
	s_mov_b32 s101, 0
	v_readfirstlane_b32 s98, v240
	s_cmp_lt_u32 s98, 64
	s_cbranch_scc0 .Lxc_join_0
	v_mov_b32_e32 v142, 0x21ffc
	ds_read_b32 v142, v142
	v_readlane_b32 s98, v253, 39
	v_readlane_b32 s99, v253, 40
	s_mov_b32 s100, 0
	s_waitcnt lgkmcnt(0)
	s_nop 4
.Lxc_spin_0:
	global_load_dword v143, v177, s[98:99] sc1
	s_waitcnt vmcnt(0)
	v_cmp_ge_u32_e32 vcc, v143, v142
	s_cbranch_vccnz .Lxc_join_0
	s_sleep 1
	s_add_i32 s100, s100, 1
	s_cmp_lt_u32 s100, 0x40000
	s_cbranch_scc1 .Lxc_spin_0

; __device__ __forceinline__ unsigned xb_ld(unsigned* p)              { return __hip_atomic_load(p, __ATOMIC_RELAXED, __HIP_MEMORY_SCOPE_AGENT); }
; __device__ __forceinline__ unsigned xb_add(unsigned* p, unsigned v) { return __hip_atomic_fetch_add(p, v, __ATOMIC_RELAXED, __HIP_MEMORY_SCOPE_AGENT); }
; #define XB_SPIN(cond, bar) do { unsigned _sp = 0; while (cond) { __builtin_amdgcn_s_sleep(1); \
;     if ((++_sp & 255u) == 0u) { if (xb_ld(&(bar)[XB_TMO])) break; if (_sp > XB_SPIN_CAP) { atomicAdd(&(bar)[XB_TMO], 1u); break; } } } } while (0)
; __device__ __forceinline__ void xcd_barrier(const XcdBarrier& b) {
;     ...
;         unsigned nloc = b.st[0], nx = b.st[1];
;         if (nloc == 0u) { xcd_barrier_complete(bar, b.x, nloc, nx); b.st[0] = nloc; b.st[1] = nx; }
;         const unsigned old = xb_add(&bar[XB_XSUB(b.x)], 1u);
;         const unsigned gen = old / nloc;
;         if (old + 1u == (gen + 1u) * nloc) {
;             __builtin_amdgcn_fence(__ATOMIC_RELEASE, "agent");
;             asm volatile("s_waitcnt vmcnt(0)" ::: "memory");
;             const unsigned og = xb_add(&bar[XB_TOP], 1u);
;             const unsigned tg = og / nx;
;             if (og + 1u == (tg + 1u) * nx) xb_add(&bar[XB_TOPGEN], 1u);
;             else XB_SPIN(xb_ld(&bar[XB_TOPGEN]) == tg, bar);
;             __builtin_amdgcn_fence(__ATOMIC_ACQUIRE, "agent");
;             asm volatile("s_waitcnt vmcnt(0)" ::: "memory");
;         } else {
;             XB_SPIN(xb_ld(&bar[XB_TOPGEN]) == gen, bar);
.LBB0_610:
	v_readlane_b32 s4, v253, 35
	v_readlane_b32 s5, v253, 36
	v_cvt_f32_u32_e32 v1, v2
	v_sub_u32_e32 v4, 0, v2
	v_rcp_iflag_f32_e32 v1, v1
	s_nop 1
	global_atomic_add v3, v177, v238, s[4:5] sc0
	buffer_inv sc1
	v_mul_f32_e32 v1, 0x4f7ffffe, v1
	v_cvt_u32_f32_e32 v1, v1
	v_mul_lo_u32 v4, v4, v1
	v_mul_hi_u32 v4, v1, v4
	v_add_u32_e32 v1, v1, v4
	s_waitcnt vmcnt(0)
	v_mul_hi_u32 v1, v3, v1
	v_mul_lo_u32 v4, v1, v2
	v_sub_u32_e32 v4, v3, v4
	v_add_u32_e32 v5, 1, v1
	v_cmp_ge_u32_e32 vcc, v4, v2
	v_add_u32_e32 v3, 1, v3
	s_nop 0
	v_cndmask_b32_e32 v1, v1, v5, vcc
	v_sub_u32_e32 v5, v4, v2
	v_cndmask_b32_e32 v4, v4, v5, vcc
	v_add_u32_e32 v5, 1, v1
	v_cmp_ge_u32_e32 vcc, v4, v2
	s_nop 1
	v_cndmask_b32_e32 v1, v1, v5, vcc
	v_mul_lo_u32 v4, v2, v1
	v_add_u32_e32 v2, v4, v2
	v_cmp_ne_u32_e32 vcc, v3, v2
	s_waitcnt lgkmcnt(0)
	v_add_u32_e32 v4, 1, v1
	v_mul_lo_u32 v4, v4, v0
	v_mov_b32_e32 v6, 0x21ff8
	ds_read_b32 v6, v6
	v_readlane_b32 s98, v253, 39
	v_readlane_b32 s99, v253, 40
	s_nop 4
	s_waitcnt lgkmcnt(0)
	v_readfirstlane_b32 s100, v6
	s_cmp_eq_u32 s100, 0
	s_cbranch_scc0 .Lxb_b3_full
	v_mov_b32_e32 v6, 0x21ffc
	ds_write_b32 v6, v4
	s_cbranch_vccnz .Lxb_b3_lnl
	s_waitcnt vmcnt(0)
	global_atomic_add v177, v238, s[98:99]
	s_branch .Lxb_b3_done

; __device__ __forceinline__ void xcd_barrier(const XcdBarrier& b) {
;     ...
;     __syncthreads();
.Lxb_b3_done:
.LBB0_642:
	s_or_b64 exec, exec, s[0:1]
	s_waitcnt lgkmcnt(0)
	s_barrier
	s_mov_b32 s101, 1
